# conv token loop: z-gate loads and output stores take base + row offset from an SGPR pair (SALU adds) and the lane offset from a VGPR; 16 64-bit VALU adds per 8 tokens removed
# baseline (speedup 1.0000x reference)
.LBB0_461:
	s_or_b64 exec, exec, s[48:49]
	v_mov_b32_e32 v112, s15
	s_waitcnt lgkmcnt(0)
	s_barrier
	ds_read_b128 v[112:115], v112
	v_mov_b32_e32 v116, s66
	ds_read_b128 v[116:119], v116
	s_waitcnt vmcnt(7)
	v_lshlrev_b32_e32 v122, 16, v216
	v_and_b32_e32 v123, 0xffff0000, v216
	s_waitcnt lgkmcnt(1)
	v_pk_add_f32 v[120:121], v[152:153], v[112:113] op_sel_hi:[1,0] neg_lo:[0,1] neg_hi:[0,1]
	s_addk_i32 s76, 0x4000
	v_pk_mul_f32 v[112:113], v[120:121], v[112:113] op_sel:[0,1]
	s_add_i32 s18, s18, 8
	v_pk_fma_f32 v[112:113], v[104:105], v[112:113], v[102:103]
	s_cmp_eq_u32 s76, 0x10000
	v_mul_f32_e32 v120, 0xbfb8aa3b, v112
	v_mul_f32_e32 v121, 0xbfb8aa3b, v113
	v_exp_f32_e32 v120, v120
	v_exp_f32_e32 v121, v121
	v_add_f32_e32 v120, 1.0, v120
	v_add_f32_e32 v121, 1.0, v121
	v_rcp_f32_e32 v120, v120
	v_rcp_f32_e32 v121, v121
	s_nop 0
	v_pk_mul_f32 v[112:113], v[112:113], v[120:121]
	s_nop 0
	v_pk_mul_f32 v[112:113], v[112:113], v[122:123]
	s_nop 0
	v_cvt_pk_bf16_f32 v122, v112, v113
	v_pk_add_f32 v[112:113], v[154:155], v[114:115] op_sel_hi:[1,0] neg_lo:[0,1] neg_hi:[0,1]
	v_mov_b32_e32 v114, v115
	v_pk_mul_f32 v[112:113], v[112:113], v[114:115] op_sel_hi:[1,0]
	s_nop 0
	v_pk_fma_f32 v[112:113], v[104:105], v[112:113], v[102:103]
	s_nop 0
	v_mul_f32_e32 v114, 0xbfb8aa3b, v112
	v_exp_f32_e32 v120, v114
	v_mul_f32_e32 v114, 0xbfb8aa3b, v113
	v_exp_f32_e32 v121, v114
	v_add_f32_e32 v120, 1.0, v120
	v_rcp_f32_e32 v120, v120
	v_add_f32_e32 v121, 1.0, v121
	v_rcp_f32_e32 v121, v121
	s_add_u32 s98, s44, s46
	s_addc_u32 s99, s45, s47
	global_store_dword v184, v122, s[98:99]
	s_waitcnt vmcnt(7)
	v_lshlrev_b32_e32 v114, 16, v215
	v_and_b32_e32 v115, 0xffff0000, v215
	v_pk_mul_f32 v[112:113], v[112:113], v[120:121]
	s_nop 0
	v_pk_mul_f32 v[112:113], v[112:113], v[114:115]
	s_nop 0
	v_cvt_pk_bf16_f32 v120, v112, v113
	s_waitcnt lgkmcnt(0)
	v_pk_add_f32 v[112:113], v[150:151], v[116:117] op_sel_hi:[1,0] neg_lo:[0,1] neg_hi:[0,1]
	s_nop 0
	v_pk_mul_f32 v[112:113], v[112:113], v[116:117] op_sel:[0,1]
	s_nop 0
	v_pk_fma_f32 v[112:113], v[104:105], v[112:113], v[102:103]
	s_nop 0
	v_mul_f32_e32 v114, 0xbfb8aa3b, v112
	v_exp_f32_e32 v116, v114
	v_mul_f32_e32 v114, 0xbfb8aa3b, v113
	v_exp_f32_e32 v117, v114
	v_add_f32_e32 v116, 1.0, v116
	v_rcp_f32_e32 v116, v116
	v_add_f32_e32 v117, 1.0, v117
	v_rcp_f32_e32 v117, v117
	s_add_u32 s98, s44, s36
	s_addc_u32 s99, s45, s37
	global_store_dword v184, v120, s[98:99]
	s_waitcnt vmcnt(7)
	v_lshlrev_b32_e32 v114, 16, v214
	v_and_b32_e32 v115, 0xffff0000, v214
	v_pk_mul_f32 v[112:113], v[112:113], v[116:117]
	s_nop 0
	v_pk_mul_f32 v[112:113], v[112:113], v[114:115]
	v_mov_b32_e32 v114, v119
	v_cvt_pk_bf16_f32 v120, v112, v113
	v_pk_add_f32 v[112:113], v[142:143], v[118:119] op_sel_hi:[1,0] neg_lo:[0,1] neg_hi:[0,1]
	s_waitcnt vmcnt(6)
	v_lshlrev_b32_e32 v118, 16, v213
	v_pk_mul_f32 v[112:113], v[112:113], v[114:115] op_sel_hi:[1,0]
	v_and_b32_e32 v119, 0xffff0000, v213
	v_pk_fma_f32 v[112:113], v[104:105], v[112:113], v[102:103]
	s_nop 0
	v_mul_f32_e32 v114, 0xbfb8aa3b, v112
	v_exp_f32_e32 v116, v114
	v_mul_f32_e32 v114, 0xbfb8aa3b, v113
	v_exp_f32_e32 v117, v114
	v_add_f32_e32 v116, 1.0, v116
	v_rcp_f32_e32 v116, v116
	v_add_f32_e32 v117, 1.0, v117
	v_rcp_f32_e32 v117, v117
	s_add_u32 s98, s44, s34
	s_addc_u32 s99, s45, s35
	global_store_dword v184, v120, s[98:99]
	v_pk_mul_f32 v[116:117], v[112:113], v[116:117]
	v_mov_b32_e32 v112, s67
	ds_read_b128 v[112:115], v112
	v_pk_mul_f32 v[116:117], v[116:117], v[118:119]
	s_nop 0
	v_cvt_pk_bf16_f32 v124, v116, v117
	v_mov_b32_e32 v116, s70
	ds_read_b128 v[116:119], v116
	s_waitcnt lgkmcnt(1)
	v_pk_add_f32 v[120:121], v[130:131], v[112:113] op_sel_hi:[1,0] neg_lo:[0,1] neg_hi:[0,1]
	s_waitcnt lgkmcnt(0)
	v_pk_add_f32 v[34:35], v[34:35], v[116:117] op_sel_hi:[1,0] neg_lo:[0,1] neg_hi:[0,1]
	v_pk_mul_f32 v[112:113], v[120:121], v[112:113] op_sel:[0,1]
	v_pk_mul_f32 v[34:35], v[34:35], v[116:117] op_sel:[0,1]
	v_pk_fma_f32 v[112:113], v[104:105], v[112:113], v[102:103]
	v_pk_fma_f32 v[34:35], v[104:105], v[34:35], v[102:103]
	v_mul_f32_e32 v120, 0xbfb8aa3b, v112
	v_exp_f32_e32 v122, v120
	v_mul_f32_e32 v120, 0xbfb8aa3b, v113
	v_exp_f32_e32 v123, v120
	v_add_f32_e32 v122, 1.0, v122
	v_rcp_f32_e32 v122, v122
	v_add_f32_e32 v123, 1.0, v123
	v_rcp_f32_e32 v123, v123
	s_add_u32 s98, s44, s30
	s_addc_u32 s99, s45, s31
	global_store_dword v184, v124, s[98:99]
	s_waitcnt vmcnt(7)
	v_lshlrev_b32_e32 v120, 16, v212
	v_and_b32_e32 v121, 0xffff0000, v212
	v_pk_mul_f32 v[112:113], v[112:113], v[122:123]
	v_pk_add_f32 v[32:33], v[32:33], v[118:119] op_sel_hi:[1,0] neg_lo:[0,1] neg_hi:[0,1]
	v_pk_mul_f32 v[112:113], v[112:113], v[120:121]
	s_nop 0
	v_cvt_pk_bf16_f32 v122, v112, v113
	v_pk_add_f32 v[112:113], v[128:129], v[114:115] op_sel_hi:[1,0] neg_lo:[0,1] neg_hi:[0,1]
	v_mov_b32_e32 v114, v115
	v_pk_mul_f32 v[112:113], v[112:113], v[114:115] op_sel_hi:[1,0]
	s_nop 0
	v_pk_fma_f32 v[112:113], v[104:105], v[112:113], v[102:103]
	s_nop 0
	v_mul_f32_e32 v114, 0xbfb8aa3b, v112
	v_exp_f32_e32 v120, v114
	v_mul_f32_e32 v114, 0xbfb8aa3b, v113
	v_exp_f32_e32 v121, v114
	v_add_f32_e32 v120, 1.0, v120
	v_rcp_f32_e32 v120, v120
	v_add_f32_e32 v121, 1.0, v121
	v_rcp_f32_e32 v121, v121
	s_add_u32 s98, s44, s28
	s_addc_u32 s99, s45, s29
	global_store_dword v184, v122, s[98:99]
	s_waitcnt vmcnt(7)
	v_lshlrev_b32_e32 v114, 16, v211
	v_and_b32_e32 v115, 0xffff0000, v211
	v_pk_mul_f32 v[112:113], v[112:113], v[120:121]
	s_nop 0
	v_pk_mul_f32 v[112:113], v[112:113], v[114:115]
	s_nop 0
	v_cvt_pk_bf16_f32 v120, v112, v113
	v_mul_f32_e32 v112, 0xbfb8aa3b, v34
	v_exp_f32_e32 v114, v112
	v_mul_f32_e32 v112, 0xbfb8aa3b, v35
	v_exp_f32_e32 v115, v112
	v_add_f32_e32 v114, 1.0, v114
	v_rcp_f32_e32 v114, v114
	v_add_f32_e32 v115, 1.0, v115
	v_rcp_f32_e32 v115, v115
	s_add_u32 s98, s44, s26
	s_addc_u32 s99, s45, s27
	global_store_dword v184, v120, s[98:99]
	s_waitcnt vmcnt(7)
	v_lshlrev_b32_e32 v112, 16, v210
	v_and_b32_e32 v113, 0xffff0000, v210
	v_pk_mul_f32 v[34:35], v[34:35], v[114:115]
	s_nop 0
	v_pk_mul_f32 v[34:35], v[34:35], v[112:113]
	s_nop 0
	v_cvt_pk_bf16_f32 v114, v34, v35
	v_mov_b32_e32 v34, v119
	v_pk_mul_f32 v[32:33], v[32:33], v[34:35] op_sel_hi:[1,0]
	s_nop 0
	v_pk_fma_f32 v[32:33], v[104:105], v[32:33], v[102:103]
	s_nop 0
	v_mul_f32_e32 v34, 0xbfb8aa3b, v32
	v_exp_f32_e32 v112, v34
	v_mul_f32_e32 v34, 0xbfb8aa3b, v33
	v_exp_f32_e32 v113, v34
	v_add_f32_e32 v112, 1.0, v112
	v_rcp_f32_e32 v112, v112
	v_add_f32_e32 v113, 1.0, v113
	v_rcp_f32_e32 v113, v113
	s_add_u32 s98, s44, s24
	s_addc_u32 s99, s45, s25
	global_store_dword v184, v114, s[98:99]
	s_waitcnt vmcnt(7)
	v_lshlrev_b32_e32 v34, 16, v209
	v_and_b32_e32 v35, 0xffff0000, v209
	v_pk_mul_f32 v[32:33], v[32:33], v[112:113]
	s_nop 0
	v_pk_mul_f32 v[32:33], v[32:33], v[34:35]
	s_nop 0
	v_cvt_pk_bf16_f32 v34, v32, v33
	s_add_u32 s98, s44, s20
	s_addc_u32 s99, s45, s21
	global_store_dword v184, v34, s[98:99]
	s_cmp_eq_u32 s76, 0x10000
	s_cbranch_scc1 .LBB0_466
.LBB0_462:
	s_add_i32 s19, s75, s76
	s_and_b32 s20, s19, 0x1c000
	v_add_u32_e32 v112, s20, v184
	ds_read2st64_b32 v[32:33], v112 offset1:8
	ds_read2st64_b32 v[34:35], v112 offset0:16 offset1:24
	s_add_i32 s21, s19, 0x4000
	s_and_b32 s21, s21, 0x1c000
	s_xor_b32 s20, s20, 0x10000
	s_waitcnt lgkmcnt(1)
	v_lshlrev_b32_e32 v152, 16, v32
	v_and_b32_e32 v153, 0xffff0000, v32
	v_lshlrev_b32_e32 v154, 16, v33
	v_and_b32_e32 v155, 0xffff0000, v33
	ds_read2st64_b32 v[32:33], v112 offset0:32 offset1:40
	ds_read2st64_b32 v[112:113], v112 offset0:48 offset1:56
	s_waitcnt lgkmcnt(2)
	v_lshlrev_b32_e32 v150, 16, v34
	v_and_b32_e32 v151, 0xffff0000, v34
	v_lshlrev_b32_e32 v142, 16, v35
	v_and_b32_e32 v143, 0xffff0000, v35
	s_waitcnt lgkmcnt(0)
	v_lshlrev_b32_e32 v34, 16, v112
	v_and_b32_e32 v35, 0xffff0000, v112
	v_add_u32_e32 v112, s21, v184
	s_add_i32 s21, s19, 0x4800
	s_and_b32 s21, s21, 0x1c800
	v_lshlrev_b32_e32 v130, 16, v32
	v_and_b32_e32 v131, 0xffff0000, v32
	v_lshlrev_b32_e32 v128, 16, v33
	v_and_b32_e32 v129, 0xffff0000, v33
	v_lshlrev_b32_e32 v32, 16, v113
	v_and_b32_e32 v33, 0xffff0000, v113
	v_add_u32_e32 v113, s21, v184
	s_add_i32 s21, s19, 0x5000
	s_and_b32 s21, s21, 0x1d000
	v_add_u32_e32 v114, s21, v184
	s_add_i32 s21, s19, 0x5800
	s_and_b32 s21, s21, 0x1d800
	v_add_u32_e32 v115, s21, v184
	s_add_i32 s21, s19, 0x6000
	s_and_b32 s21, s21, 0x1e000
	v_add_u32_e32 v116, s21, v184
	s_add_i32 s21, s19, 0x6800
	s_and_b32 s21, s21, 0x1e800
	v_add_u32_e32 v117, s21, v184
	s_add_i32 s21, s19, 0x7000
	s_and_b32 s21, s21, 0x1f000
	v_add_u32_e32 v118, s21, v184
	s_add_i32 s21, s19, 0x7800
	s_and_b32 s21, s21, 0x1f800
	v_add_u32_e32 v119, s21, v184
	s_add_i32 s21, s19, 0x8000
	s_and_b32 s21, s21, 0x1c000
	v_add_u32_e32 v132, s21, v184
	s_add_i32 s21, s19, 0x8800
	s_and_b32 s21, s21, 0x1c800
	v_add_u32_e32 v133, s21, v184
	s_add_i32 s21, s19, 0x9000
	s_and_b32 s21, s21, 0x1d000
	v_add_u32_e32 v134, s21, v184
	s_add_i32 s21, s19, 0x9800
	s_and_b32 s21, s21, 0x1d800
	v_add_u32_e32 v135, s21, v184
	s_add_i32 s21, s19, 0xa000
	s_and_b32 s21, s21, 0x1e000
	v_add_u32_e32 v136, s21, v184
	s_add_i32 s21, s19, 0xa800
	s_and_b32 s21, s21, 0x1e800
	v_add_u32_e32 v137, s21, v184
	s_add_i32 s21, s19, 0xb000
	s_and_b32 s21, s21, 0x1f000
	v_add_u32_e32 v138, s21, v184
	s_add_i32 s21, s19, 0xb800
	s_and_b32 s21, s21, 0x1f800
	v_add_u32_e32 v139, s21, v184
	s_add_i32 s21, s19, 0xc000
	s_and_b32 s21, s21, 0x1c000
	v_add_u32_e32 v156, s21, v184
	s_add_i32 s21, s19, 0xc800
	s_and_b32 s21, s21, 0x1c800
	v_add_u32_e32 v157, s21, v184
	s_add_i32 s21, s19, 0xd000
	s_and_b32 s21, s21, 0x1d000
	v_add_u32_e32 v158, s21, v184
	s_add_i32 s21, s19, 0xd800
	s_and_b32 s21, s21, 0x1d800
	v_add_u32_e32 v159, s21, v184
	s_add_i32 s21, s19, 0xe000
	s_and_b32 s21, s21, 0x1e000
	v_add_u32_e32 v160, s21, v184
	s_add_i32 s21, s19, 0xe800
	s_and_b32 s21, s21, 0x1e800
	v_add_u32_e32 v161, s21, v184
	s_add_i32 s21, s19, 0xf000
	s_and_b32 s21, s21, 0x1f000
	v_add_u32_e32 v172, s20, v184
	s_add_i32 s20, s19, 0x11000
	v_add_u32_e32 v162, s21, v184
	s_add_i32 s21, s19, 0xf800
	s_and_b32 s20, s20, 0x1d000
	s_and_b32 s21, s21, 0x1f800
	v_add_u32_e32 v174, s20, v184
	s_add_i32 s20, s18, -7
	v_add_u32_e32 v163, s21, v184
	s_ashr_i32 s21, s20, 31
	s_lshl_b64 s[46:47], s[20:21], 11
	s_add_i32 s20, s18, -6
	s_ashr_i32 s21, s20, 31
	s_lshl_b64 s[36:37], s[20:21], 11
	s_add_i32 s20, s18, -5
	s_ashr_i32 s21, s20, 31
	s_lshl_b64 s[34:35], s[20:21], 11
	s_add_i32 s20, s18, -4
	s_ashr_i32 s21, s20, 31
	s_add_i32 s19, s19, 0x12000
	s_lshl_b64 s[30:31], s[20:21], 11
	s_add_i32 s20, s18, -3
	ds_read_b32 v120, v112
	ds_read_b32 v121, v113
	ds_read_b32 v122, v114
	ds_read_b32 v123, v115
	ds_read_b32 v124, v116
	ds_read_b32 v125, v117
	ds_read_b32 v126, v118
	ds_read_b32 v127, v119
	ds_read_b32 v140, v132
	ds_read_b32 v141, v133
	ds_read_b32 v144, v134
	ds_read_b32 v145, v135
	ds_read_b32 v146, v136
	ds_read_b32 v147, v137
	ds_read_b32 v148, v138
	ds_read_b32 v149, v139
	ds_read_b32 v164, v156
	ds_read_b32 v165, v157
	ds_read_b32 v166, v158
	ds_read_b32 v167, v159
	ds_read_b32 v168, v160
	ds_read_b32 v169, v161
	ds_read_b32 v170, v162
	ds_read_b32 v171, v163
	ds_read_b32 v173, v172
	v_add_u32_e32 v172, s76, v208
	s_and_b32 s19, s19, 0x1e000
	s_ashr_i32 s21, s20, 31
	ds_read2st64_b32 v[178:179], v172 offset1:16
	v_add_u32_e32 v175, s19, v184
	ds_read_b32 v177, v174
	ds_read_b32 v183, v175
	ds_read_b32 v209, v172 offset:8192
	s_lshl_b64 s[28:29], s[20:21], 11
	s_add_i32 s20, s18, -2
	v_pk_fma_f32 v[152:153], v[98:99], v[152:153], v[100:101]
	s_ashr_i32 s21, s20, 31
	v_pk_fma_f32 v[152:153], v[38:39], v[154:155], v[152:153]
	v_pk_fma_f32 v[154:155], v[98:99], v[154:155], v[100:101]
	s_lshl_b64 s[26:27], s[20:21], 11
	s_add_i32 s20, s18, -1
	v_pk_fma_f32 v[152:153], v[40:41], v[150:151], v[152:153]
	v_pk_fma_f32 v[154:155], v[38:39], v[150:151], v[154:155]
	v_pk_fma_f32 v[150:151], v[98:99], v[150:151], v[100:101]
	s_ashr_i32 s21, s20, 31
	s_ashr_i32 s19, s18, 31
	v_pk_fma_f32 v[152:153], v[42:43], v[142:143], v[152:153]
	v_pk_fma_f32 v[154:155], v[40:41], v[142:143], v[154:155]
	v_pk_fma_f32 v[150:151], v[38:39], v[142:143], v[150:151]
	v_pk_fma_f32 v[142:143], v[98:99], v[142:143], v[100:101]
	s_lshl_b64 s[24:25], s[20:21], 11
	s_lshl_b64 s[20:21], s[18:19], 11
	v_pk_fma_f32 v[152:153], v[44:45], v[130:131], v[152:153]
	v_pk_fma_f32 v[154:155], v[42:43], v[130:131], v[154:155]
	v_pk_fma_f32 v[150:151], v[40:41], v[130:131], v[150:151]
	v_pk_fma_f32 v[142:143], v[38:39], v[130:131], v[142:143]
	v_pk_fma_f32 v[130:131], v[98:99], v[130:131], v[100:101]
	s_waitcnt lgkmcnt(3)
	v_lshlrev_b32_e32 v174, 16, v178
	v_and_b32_e32 v175, 0xffff0000, v178
	v_lshlrev_b32_e32 v180, 16, v179
	v_and_b32_e32 v181, 0xffff0000, v179
	s_waitcnt lgkmcnt(0)
	v_lshlrev_b32_e32 v178, 16, v209
	v_and_b32_e32 v179, 0xffff0000, v209
	s_add_u32 s98, s0, s46
	s_addc_u32 s99, s1, s47
	global_load_dword v216, v184, s[98:99] nt
	s_add_u32 s98, s0, s36
	s_addc_u32 s99, s1, s37
	global_load_dword v215, v184, s[98:99] nt
	s_add_u32 s98, s0, s34
	s_addc_u32 s99, s1, s35
	global_load_dword v214, v184, s[98:99] nt
	s_nop 0
	s_add_u32 s98, s0, s30
	s_addc_u32 s99, s1, s31
	global_load_dword v213, v184, s[98:99] nt
	s_add_u32 s98, s0, s28
	s_addc_u32 s99, s1, s29
	global_load_dword v212, v184, s[98:99] nt
	s_add_u32 s98, s0, s26
	s_addc_u32 s99, s1, s27
	global_load_dword v211, v184, s[98:99] nt
	s_add_u32 s98, s0, s24
	s_addc_u32 s99, s1, s25
	global_load_dword v210, v184, s[98:99] nt
	s_add_u32 s98, s0, s20
	s_addc_u32 s99, s1, s21
	global_load_dword v209, v184, s[98:99] nt
	v_pk_fma_f32 v[152:153], v[46:47], v[128:129], v[152:153]
	v_pk_fma_f32 v[154:155], v[44:45], v[128:129], v[154:155]
	v_pk_fma_f32 v[150:151], v[42:43], v[128:129], v[150:151]
	v_pk_fma_f32 v[142:143], v[40:41], v[128:129], v[142:143]
	v_pk_fma_f32 v[130:131], v[38:39], v[128:129], v[130:131]
	v_pk_fma_f32 v[128:129], v[98:99], v[128:129], v[100:101]
	v_pk_fma_f32 v[152:153], v[48:49], v[34:35], v[152:153]
	v_pk_fma_f32 v[154:155], v[46:47], v[34:35], v[154:155]
	v_pk_fma_f32 v[150:151], v[44:45], v[34:35], v[150:151]
	v_pk_fma_f32 v[142:143], v[42:43], v[34:35], v[142:143]
	v_pk_fma_f32 v[130:131], v[40:41], v[34:35], v[130:131]
	v_pk_fma_f32 v[128:129], v[38:39], v[34:35], v[128:129]
	v_pk_fma_f32 v[34:35], v[98:99], v[34:35], v[100:101]
	v_lshlrev_b32_e32 v112, 16, v120
	v_and_b32_e32 v113, 0xffff0000, v120
	v_pk_fma_f32 v[152:153], v[50:51], v[32:33], v[152:153]
	v_pk_fma_f32 v[154:155], v[48:49], v[32:33], v[154:155]
	v_pk_fma_f32 v[150:151], v[46:47], v[32:33], v[150:151]
	v_pk_fma_f32 v[142:143], v[44:45], v[32:33], v[142:143]
	v_pk_fma_f32 v[130:131], v[42:43], v[32:33], v[130:131]
	v_pk_fma_f32 v[128:129], v[40:41], v[32:33], v[128:129]
	v_pk_fma_f32 v[34:35], v[38:39], v[32:33], v[34:35]
	v_pk_fma_f32 v[32:33], v[98:99], v[32:33], v[100:101]
	v_lshlrev_b32_e32 v114, 16, v121
	v_and_b32_e32 v115, 0xffff0000, v121
	v_pk_fma_f32 v[152:153], v[52:53], v[112:113], v[152:153]
	v_pk_fma_f32 v[154:155], v[50:51], v[112:113], v[154:155]
	v_pk_fma_f32 v[150:151], v[48:49], v[112:113], v[150:151]
	v_pk_fma_f32 v[142:143], v[46:47], v[112:113], v[142:143]
	v_pk_fma_f32 v[130:131], v[44:45], v[112:113], v[130:131]
	v_pk_fma_f32 v[128:129], v[42:43], v[112:113], v[128:129]
	v_pk_fma_f32 v[34:35], v[40:41], v[112:113], v[34:35]
	v_pk_fma_f32 v[32:33], v[38:39], v[112:113], v[32:33]
	v_lshlrev_b32_e32 v116, 16, v122
	v_and_b32_e32 v117, 0xffff0000, v122
	v_pk_fma_f32 v[152:153], v[54:55], v[114:115], v[152:153]
	v_pk_fma_f32 v[154:155], v[52:53], v[114:115], v[154:155]
	v_pk_fma_f32 v[150:151], v[50:51], v[114:115], v[150:151]
	v_pk_fma_f32 v[142:143], v[48:49], v[114:115], v[142:143]
	v_pk_fma_f32 v[130:131], v[46:47], v[114:115], v[130:131]
	v_pk_fma_f32 v[128:129], v[44:45], v[114:115], v[128:129]
	v_pk_fma_f32 v[34:35], v[42:43], v[114:115], v[34:35]
	v_pk_fma_f32 v[32:33], v[40:41], v[114:115], v[32:33]
	v_lshlrev_b32_e32 v118, 16, v123
	v_and_b32_e32 v119, 0xffff0000, v123
	v_pk_fma_f32 v[152:153], v[56:57], v[116:117], v[152:153]
	v_pk_fma_f32 v[154:155], v[54:55], v[116:117], v[154:155]
	v_pk_fma_f32 v[150:151], v[52:53], v[116:117], v[150:151]
	v_pk_fma_f32 v[142:143], v[50:51], v[116:117], v[142:143]
	v_pk_fma_f32 v[130:131], v[48:49], v[116:117], v[130:131]
	v_pk_fma_f32 v[128:129], v[46:47], v[116:117], v[128:129]
	v_pk_fma_f32 v[34:35], v[44:45], v[116:117], v[34:35]
	v_pk_fma_f32 v[32:33], v[42:43], v[116:117], v[32:33]
	v_lshlrev_b32_e32 v120, 16, v124
	v_and_b32_e32 v121, 0xffff0000, v124
	v_pk_fma_f32 v[152:153], v[58:59], v[118:119], v[152:153]
	v_pk_fma_f32 v[154:155], v[56:57], v[118:119], v[154:155]
	v_pk_fma_f32 v[150:151], v[54:55], v[118:119], v[150:151]
	v_pk_fma_f32 v[142:143], v[52:53], v[118:119], v[142:143]
	v_pk_fma_f32 v[130:131], v[50:51], v[118:119], v[130:131]
	v_pk_fma_f32 v[128:129], v[48:49], v[118:119], v[128:129]
	v_pk_fma_f32 v[34:35], v[46:47], v[118:119], v[34:35]
	v_pk_fma_f32 v[32:33], v[44:45], v[118:119], v[32:33]
	v_lshlrev_b32_e32 v122, 16, v125
	v_and_b32_e32 v123, 0xffff0000, v125
	v_pk_fma_f32 v[152:153], v[60:61], v[120:121], v[152:153]
	v_pk_fma_f32 v[154:155], v[58:59], v[120:121], v[154:155]
	v_pk_fma_f32 v[150:151], v[56:57], v[120:121], v[150:151]
	v_pk_fma_f32 v[142:143], v[54:55], v[120:121], v[142:143]
	v_pk_fma_f32 v[130:131], v[52:53], v[120:121], v[130:131]
	v_pk_fma_f32 v[128:129], v[50:51], v[120:121], v[128:129]
	v_pk_fma_f32 v[34:35], v[48:49], v[120:121], v[34:35]
	v_pk_fma_f32 v[32:33], v[46:47], v[120:121], v[32:33]
	v_lshlrev_b32_e32 v124, 16, v126
	v_and_b32_e32 v125, 0xffff0000, v126
	v_pk_fma_f32 v[152:153], v[62:63], v[122:123], v[152:153]
	v_pk_fma_f32 v[154:155], v[60:61], v[122:123], v[154:155]
	v_pk_fma_f32 v[150:151], v[58:59], v[122:123], v[150:151]
	v_pk_fma_f32 v[142:143], v[56:57], v[122:123], v[142:143]
	v_pk_fma_f32 v[130:131], v[54:55], v[122:123], v[130:131]
	v_pk_fma_f32 v[128:129], v[52:53], v[122:123], v[128:129]
	v_pk_fma_f32 v[34:35], v[50:51], v[122:123], v[34:35]
	v_pk_fma_f32 v[32:33], v[48:49], v[122:123], v[32:33]
	v_lshlrev_b32_e32 v126, 16, v127
	v_and_b32_e32 v127, 0xffff0000, v127
	v_pk_fma_f32 v[152:153], v[64:65], v[124:125], v[152:153]
	v_pk_fma_f32 v[154:155], v[62:63], v[124:125], v[154:155]
	v_pk_fma_f32 v[150:151], v[60:61], v[124:125], v[150:151]
	v_pk_fma_f32 v[142:143], v[58:59], v[124:125], v[142:143]
	v_pk_fma_f32 v[130:131], v[56:57], v[124:125], v[130:131]
	v_pk_fma_f32 v[128:129], v[54:55], v[124:125], v[128:129]
	v_pk_fma_f32 v[34:35], v[52:53], v[124:125], v[34:35]
	v_pk_fma_f32 v[32:33], v[50:51], v[124:125], v[32:33]
	v_lshlrev_b32_e32 v132, 16, v140
	v_and_b32_e32 v133, 0xffff0000, v140
	v_pk_fma_f32 v[152:153], v[66:67], v[126:127], v[152:153]
	v_pk_fma_f32 v[154:155], v[64:65], v[126:127], v[154:155]
	v_pk_fma_f32 v[150:151], v[62:63], v[126:127], v[150:151]
	v_pk_fma_f32 v[142:143], v[60:61], v[126:127], v[142:143]
	v_pk_fma_f32 v[130:131], v[58:59], v[126:127], v[130:131]
	v_pk_fma_f32 v[128:129], v[56:57], v[126:127], v[128:129]
	v_pk_fma_f32 v[34:35], v[54:55], v[126:127], v[34:35]
	v_pk_fma_f32 v[32:33], v[52:53], v[126:127], v[32:33]
	v_lshlrev_b32_e32 v134, 16, v141
	v_and_b32_e32 v135, 0xffff0000, v141
	v_pk_fma_f32 v[152:153], v[68:69], v[132:133], v[152:153]
	v_pk_fma_f32 v[154:155], v[66:67], v[132:133], v[154:155]
	v_pk_fma_f32 v[150:151], v[64:65], v[132:133], v[150:151]
	v_pk_fma_f32 v[142:143], v[62:63], v[132:133], v[142:143]
	v_pk_fma_f32 v[130:131], v[60:61], v[132:133], v[130:131]
	v_pk_fma_f32 v[128:129], v[58:59], v[132:133], v[128:129]
	v_pk_fma_f32 v[34:35], v[56:57], v[132:133], v[34:35]
	v_pk_fma_f32 v[32:33], v[54:55], v[132:133], v[32:33]
	v_lshlrev_b32_e32 v136, 16, v144
	v_and_b32_e32 v137, 0xffff0000, v144
	v_pk_fma_f32 v[152:153], v[70:71], v[134:135], v[152:153]
	v_pk_fma_f32 v[154:155], v[68:69], v[134:135], v[154:155]
	v_pk_fma_f32 v[150:151], v[66:67], v[134:135], v[150:151]
	v_pk_fma_f32 v[142:143], v[64:65], v[134:135], v[142:143]
	v_pk_fma_f32 v[130:131], v[62:63], v[134:135], v[130:131]
	v_pk_fma_f32 v[128:129], v[60:61], v[134:135], v[128:129]
	v_pk_fma_f32 v[34:35], v[58:59], v[134:135], v[34:35]
	v_pk_fma_f32 v[32:33], v[56:57], v[134:135], v[32:33]
	v_lshlrev_b32_e32 v138, 16, v145
	v_and_b32_e32 v139, 0xffff0000, v145
	v_pk_fma_f32 v[152:153], v[72:73], v[136:137], v[152:153]
	v_pk_fma_f32 v[154:155], v[70:71], v[136:137], v[154:155]
	v_pk_fma_f32 v[150:151], v[68:69], v[136:137], v[150:151]
	v_pk_fma_f32 v[142:143], v[66:67], v[136:137], v[142:143]
	v_pk_fma_f32 v[130:131], v[64:65], v[136:137], v[130:131]
	v_pk_fma_f32 v[128:129], v[62:63], v[136:137], v[128:129]
	v_pk_fma_f32 v[34:35], v[60:61], v[136:137], v[34:35]
	v_pk_fma_f32 v[32:33], v[58:59], v[136:137], v[32:33]
	v_lshlrev_b32_e32 v140, 16, v146
	v_and_b32_e32 v141, 0xffff0000, v146
	v_pk_fma_f32 v[152:153], v[74:75], v[138:139], v[152:153]
	v_pk_fma_f32 v[154:155], v[72:73], v[138:139], v[154:155]
	v_pk_fma_f32 v[150:151], v[70:71], v[138:139], v[150:151]
	v_pk_fma_f32 v[142:143], v[68:69], v[138:139], v[142:143]
	v_pk_fma_f32 v[130:131], v[66:67], v[138:139], v[130:131]
	v_pk_fma_f32 v[128:129], v[64:65], v[138:139], v[128:129]
	v_pk_fma_f32 v[34:35], v[62:63], v[138:139], v[34:35]
	v_pk_fma_f32 v[32:33], v[60:61], v[138:139], v[32:33]
	v_lshlrev_b32_e32 v144, 16, v147
	v_and_b32_e32 v145, 0xffff0000, v147
	v_pk_fma_f32 v[152:153], v[76:77], v[140:141], v[152:153]
	v_pk_fma_f32 v[154:155], v[74:75], v[140:141], v[154:155]
	v_pk_fma_f32 v[150:151], v[72:73], v[140:141], v[150:151]
	v_pk_fma_f32 v[142:143], v[70:71], v[140:141], v[142:143]
	v_pk_fma_f32 v[130:131], v[68:69], v[140:141], v[130:131]
	v_pk_fma_f32 v[128:129], v[66:67], v[140:141], v[128:129]
	v_pk_fma_f32 v[34:35], v[64:65], v[140:141], v[34:35]
	v_pk_fma_f32 v[32:33], v[62:63], v[140:141], v[32:33]
	v_lshlrev_b32_e32 v146, 16, v148
	v_and_b32_e32 v147, 0xffff0000, v148
	v_pk_fma_f32 v[152:153], v[78:79], v[144:145], v[152:153]
	v_pk_fma_f32 v[154:155], v[76:77], v[144:145], v[154:155]
	v_pk_fma_f32 v[150:151], v[74:75], v[144:145], v[150:151]
	v_pk_fma_f32 v[142:143], v[72:73], v[144:145], v[142:143]
	v_pk_fma_f32 v[130:131], v[70:71], v[144:145], v[130:131]
	v_pk_fma_f32 v[128:129], v[68:69], v[144:145], v[128:129]
	v_pk_fma_f32 v[34:35], v[66:67], v[144:145], v[34:35]
	v_pk_fma_f32 v[32:33], v[64:65], v[144:145], v[32:33]
	v_lshlrev_b32_e32 v148, 16, v149
	v_and_b32_e32 v149, 0xffff0000, v149
	v_pk_fma_f32 v[152:153], v[80:81], v[146:147], v[152:153]
	v_pk_fma_f32 v[154:155], v[78:79], v[146:147], v[154:155]
	v_pk_fma_f32 v[150:151], v[76:77], v[146:147], v[150:151]
	v_pk_fma_f32 v[142:143], v[74:75], v[146:147], v[142:143]
	v_pk_fma_f32 v[130:131], v[72:73], v[146:147], v[130:131]
	v_pk_fma_f32 v[128:129], v[70:71], v[146:147], v[128:129]
	v_pk_fma_f32 v[34:35], v[68:69], v[146:147], v[34:35]
	v_pk_fma_f32 v[32:33], v[66:67], v[146:147], v[32:33]
	v_lshlrev_b32_e32 v156, 16, v164
	v_and_b32_e32 v157, 0xffff0000, v164
	v_pk_fma_f32 v[152:153], v[82:83], v[148:149], v[152:153]
	v_pk_fma_f32 v[154:155], v[80:81], v[148:149], v[154:155]
	v_pk_fma_f32 v[150:151], v[78:79], v[148:149], v[150:151]
	v_pk_fma_f32 v[142:143], v[76:77], v[148:149], v[142:143]
	v_pk_fma_f32 v[130:131], v[74:75], v[148:149], v[130:131]
	v_pk_fma_f32 v[128:129], v[72:73], v[148:149], v[128:129]
	v_pk_fma_f32 v[34:35], v[70:71], v[148:149], v[34:35]
	v_pk_fma_f32 v[32:33], v[68:69], v[148:149], v[32:33]
	v_lshlrev_b32_e32 v158, 16, v165
	v_and_b32_e32 v159, 0xffff0000, v165
	v_pk_fma_f32 v[152:153], v[84:85], v[156:157], v[152:153]
	v_pk_fma_f32 v[154:155], v[82:83], v[156:157], v[154:155]
	v_pk_fma_f32 v[150:151], v[80:81], v[156:157], v[150:151]
	v_pk_fma_f32 v[142:143], v[78:79], v[156:157], v[142:143]
	v_pk_fma_f32 v[130:131], v[76:77], v[156:157], v[130:131]
	v_pk_fma_f32 v[128:129], v[74:75], v[156:157], v[128:129]
	v_pk_fma_f32 v[34:35], v[72:73], v[156:157], v[34:35]
	v_pk_fma_f32 v[32:33], v[70:71], v[156:157], v[32:33]
	v_lshlrev_b32_e32 v160, 16, v166
	v_and_b32_e32 v161, 0xffff0000, v166
	v_pk_fma_f32 v[152:153], v[86:87], v[158:159], v[152:153]
	v_pk_fma_f32 v[154:155], v[84:85], v[158:159], v[154:155]
	v_pk_fma_f32 v[150:151], v[82:83], v[158:159], v[150:151]
	v_pk_fma_f32 v[142:143], v[80:81], v[158:159], v[142:143]
	v_pk_fma_f32 v[130:131], v[78:79], v[158:159], v[130:131]
	v_pk_fma_f32 v[128:129], v[76:77], v[158:159], v[128:129]
	v_pk_fma_f32 v[34:35], v[74:75], v[158:159], v[34:35]
	v_pk_fma_f32 v[32:33], v[72:73], v[158:159], v[32:33]
	v_lshlrev_b32_e32 v162, 16, v167
	v_and_b32_e32 v163, 0xffff0000, v167
	v_pk_fma_f32 v[152:153], v[88:89], v[160:161], v[152:153]
	v_pk_fma_f32 v[154:155], v[86:87], v[160:161], v[154:155]
	v_pk_fma_f32 v[150:151], v[84:85], v[160:161], v[150:151]
	v_pk_fma_f32 v[142:143], v[82:83], v[160:161], v[142:143]
	v_pk_fma_f32 v[130:131], v[80:81], v[160:161], v[130:131]
	v_pk_fma_f32 v[128:129], v[78:79], v[160:161], v[128:129]
	v_pk_fma_f32 v[34:35], v[76:77], v[160:161], v[34:35]
	v_pk_fma_f32 v[32:33], v[74:75], v[160:161], v[32:33]
	v_lshlrev_b32_e32 v164, 16, v168
	v_and_b32_e32 v165, 0xffff0000, v168
	v_pk_fma_f32 v[152:153], v[90:91], v[162:163], v[152:153]
	v_pk_fma_f32 v[154:155], v[88:89], v[162:163], v[154:155]
	v_pk_fma_f32 v[150:151], v[86:87], v[162:163], v[150:151]
	v_pk_fma_f32 v[142:143], v[84:85], v[162:163], v[142:143]
	v_pk_fma_f32 v[130:131], v[82:83], v[162:163], v[130:131]
	v_pk_fma_f32 v[128:129], v[80:81], v[162:163], v[128:129]
	v_pk_fma_f32 v[34:35], v[78:79], v[162:163], v[34:35]
	v_pk_fma_f32 v[32:33], v[76:77], v[162:163], v[32:33]
	v_lshlrev_b32_e32 v166, 16, v169
	v_and_b32_e32 v167, 0xffff0000, v169
	v_pk_fma_f32 v[152:153], v[92:93], v[164:165], v[152:153]
	v_pk_fma_f32 v[154:155], v[90:91], v[164:165], v[154:155]
	v_pk_fma_f32 v[150:151], v[88:89], v[164:165], v[150:151]
	v_pk_fma_f32 v[142:143], v[86:87], v[164:165], v[142:143]
	v_pk_fma_f32 v[130:131], v[84:85], v[164:165], v[130:131]
	v_pk_fma_f32 v[128:129], v[82:83], v[164:165], v[128:129]
	v_pk_fma_f32 v[34:35], v[80:81], v[164:165], v[34:35]
	v_pk_fma_f32 v[32:33], v[78:79], v[164:165], v[32:33]
	v_lshlrev_b32_e32 v168, 16, v170
	v_and_b32_e32 v169, 0xffff0000, v170
	v_pk_fma_f32 v[152:153], v[94:95], v[166:167], v[152:153]
	v_pk_fma_f32 v[154:155], v[92:93], v[166:167], v[154:155]
	v_pk_fma_f32 v[150:151], v[90:91], v[166:167], v[150:151]
	v_pk_fma_f32 v[142:143], v[88:89], v[166:167], v[142:143]
	v_pk_fma_f32 v[130:131], v[86:87], v[166:167], v[130:131]
	v_pk_fma_f32 v[128:129], v[84:85], v[166:167], v[128:129]
	v_pk_fma_f32 v[34:35], v[82:83], v[166:167], v[34:35]
	v_pk_fma_f32 v[32:33], v[80:81], v[166:167], v[32:33]
	v_lshlrev_b32_e32 v170, 16, v171
	v_and_b32_e32 v171, 0xffff0000, v171
	v_pk_fma_f32 v[152:153], v[96:97], v[168:169], v[152:153]
	v_pk_fma_f32 v[154:155], v[94:95], v[168:169], v[154:155]
	v_pk_fma_f32 v[150:151], v[92:93], v[168:169], v[150:151]
	v_pk_fma_f32 v[142:143], v[90:91], v[168:169], v[142:143]
	v_pk_fma_f32 v[130:131], v[88:89], v[168:169], v[130:131]
	v_pk_fma_f32 v[128:129], v[86:87], v[168:169], v[128:129]
	v_pk_fma_f32 v[34:35], v[84:85], v[168:169], v[34:35]
	v_pk_fma_f32 v[32:33], v[82:83], v[168:169], v[32:33]
	v_lshlrev_b32_e32 v172, 16, v173
	v_and_b32_e32 v173, 0xffff0000, v173
	v_pk_fma_f32 v[154:155], v[96:97], v[170:171], v[154:155]
	v_pk_fma_f32 v[150:151], v[94:95], v[170:171], v[150:151]
	v_pk_fma_f32 v[142:143], v[92:93], v[170:171], v[142:143]
	v_pk_fma_f32 v[130:131], v[90:91], v[170:171], v[130:131]
	v_pk_fma_f32 v[128:129], v[88:89], v[170:171], v[128:129]
	v_pk_fma_f32 v[34:35], v[86:87], v[170:171], v[34:35]
	v_pk_fma_f32 v[32:33], v[84:85], v[170:171], v[32:33]
	v_pk_mul_f32 v[112:113], v[152:153], v[152:153]
	v_pk_fma_f32 v[150:151], v[96:97], v[172:173], v[150:151]
	v_pk_fma_f32 v[142:143], v[94:95], v[172:173], v[142:143]
	v_pk_fma_f32 v[130:131], v[92:93], v[172:173], v[130:131]
	v_pk_fma_f32 v[128:129], v[90:91], v[172:173], v[128:129]
	v_pk_fma_f32 v[34:35], v[88:89], v[172:173], v[34:35]
	v_pk_fma_f32 v[32:33], v[86:87], v[172:173], v[32:33]
	v_add_f32_e32 v115, v112, v113
	v_pk_mul_f32 v[112:113], v[154:155], v[154:155]
	v_lshlrev_b32_e32 v176, 16, v177
	v_and_b32_e32 v177, 0xffff0000, v177
	v_pk_fma_f32 v[142:143], v[96:97], v[174:175], v[142:143]
	v_pk_fma_f32 v[130:131], v[94:95], v[174:175], v[130:131]
	v_pk_fma_f32 v[128:129], v[92:93], v[174:175], v[128:129]
	v_pk_fma_f32 v[34:35], v[90:91], v[174:175], v[34:35]
	v_pk_fma_f32 v[32:33], v[88:89], v[174:175], v[32:33]
	v_add_f32_e32 v117, v112, v113
	v_pk_mul_f32 v[112:113], v[150:151], v[150:151]
	v_pk_fma_f32 v[130:131], v[96:97], v[176:177], v[130:131]
	v_pk_fma_f32 v[128:129], v[94:95], v[176:177], v[128:129]
	v_pk_fma_f32 v[34:35], v[92:93], v[176:177], v[34:35]
	v_pk_fma_f32 v[32:33], v[90:91], v[176:177], v[32:33]
	v_add_f32_e32 v119, v112, v113
	v_pk_mul_f32 v[112:113], v[142:143], v[142:143]
	v_lshlrev_b32_e32 v182, 16, v183
	v_and_b32_e32 v183, 0xffff0000, v183
	v_pk_fma_f32 v[128:129], v[96:97], v[180:181], v[128:129]
	v_pk_fma_f32 v[34:35], v[94:95], v[180:181], v[34:35]
	v_pk_fma_f32 v[32:33], v[92:93], v[180:181], v[32:33]
	v_add_f32_e32 v121, v112, v113
	v_pk_mul_f32 v[112:113], v[130:131], v[130:131]
	v_pk_fma_f32 v[34:35], v[96:97], v[182:183], v[34:35]
	v_pk_fma_f32 v[32:33], v[94:95], v[182:183], v[32:33]
	v_add_f32_e32 v123, v112, v113
	v_pk_mul_f32 v[112:113], v[128:129], v[128:129]
	v_pk_fma_f32 v[32:33], v[96:97], v[178:179], v[32:33]
	v_add_f32_e32 v125, v112, v113
	v_pk_mul_f32 v[112:113], v[34:35], v[34:35]
	v_add_f32_e32 v114, v152, v153
	v_add_f32_e32 v122, v130, v131
	v_add_f32_e32 v127, v112, v113
	v_pk_mul_f32 v[112:113], v[32:33], v[32:33]
	v_add_f32_e32 v116, v154, v155
	v_add_f32_e32 v112, v112, v113
	v_add_f32_e32 v124, v128, v129
	v_add_f32_e32 v118, v150, v151
	v_add_f32_e32 v126, v34, v35
	v_add_f32_e32 v120, v142, v143
	v_add_f32_e32 v132, v32, v33
	s_nop 1
	v_permlane32_swap_b32_e32 v114, v122
	v_permlane32_swap_b32_e32 v115, v123
	v_permlane32_swap_b32_e32 v116, v124
	v_permlane32_swap_b32_e32 v117, v125
	v_permlane32_swap_b32_e32 v118, v126
	v_permlane32_swap_b32_e32 v119, v127
	v_permlane32_swap_b32_e32 v120, v132
	v_permlane32_swap_b32_e32 v121, v112
	v_add_f32_e32 v114, v114, v122
	v_add_f32_e32 v115, v115, v123
	v_add_f32_e32 v116, v116, v124
	v_add_f32_e32 v117, v117, v125
	v_add_f32_e32 v118, v118, v126
	v_add_f32_e32 v119, v119, v127
	v_add_f32_e32 v120, v120, v132
	v_add_f32_e32 v121, v121, v112
	s_nop 1
	v_permlane16_swap_b32_e32 v114, v118
	v_permlane16_swap_b32_e32 v115, v119
	v_permlane16_swap_b32_e32 v116, v120
	v_permlane16_swap_b32_e32 v117, v121
	v_add_f32_e32 v114, v114, v118
	v_add_f32_e32 v115, v115, v119
	v_add_f32_e32 v116, v116, v120
	v_add_f32_e32 v117, v117, v121
	s_nop 1
	v_add_f32_dpp v122, v114, v114 row_ror:8 row_mask:0xf bank_mask:0xf
	v_add_f32_dpp v123, v116, v116 row_ror:8 row_mask:0xf bank_mask:0xf
	v_add_f32_dpp v124, v115, v115 row_ror:8 row_mask:0xf bank_mask:0xf
	v_add_f32_dpp v125, v117, v117 row_ror:8 row_mask:0xf bank_mask:0xf
	v_cndmask_b32_e64 v114, v123, v122, s[6:7]
	v_cndmask_b32_e64 v115, v125, v124, s[6:7]
	s_nop 1
	v_add_f32_dpp v122, v114, v114 row_shl:4 row_mask:0xf bank_mask:0xf
	v_add_f32_dpp v123, v115, v115 row_shr:4 row_mask:0xf bank_mask:0xf
	v_cndmask_b32_e64 v112, v123, v122, s[8:9]
	s_nop 1
	v_add_f32_dpp v112, v112, v112 quad_perm:[2,3,0,1] row_mask:0xf bank_mask:0xf
	s_nop 1
	v_add_f32_dpp v112, v112, v112 quad_perm:[1,0,3,2] row_mask:0xf bank_mask:0xf
	s_and_saveexec_b64 s[48:49], s[10:11]
	s_cbranch_execz .LBB0_464
	ds_write_b32 v185, v112
